# P4 epilogue: removed 128 redundant v_max canonicalize ops per tile (folded into relu max), hazard-padded
# baseline (speedup 1.0000x reference)
; __device__ __forceinline__ unsigned cvt_pk_bf16(float lo, float hi) { unsigned r; asm volatile("v_cvt_pk_bf16_f32 %0, %1, %2" : "=v"(r) : "v"(lo), "v"(hi)); return r; }
;     __device__ __forceinline__ void operator()(const f32x4 (&acc)[2][2][4][2], const Unit& u, int wr, int wc, int fr, int fq) const {
;     ...
;             for (int m = 0; m < 4; ++m) pv[ai][m] = __builtin_nontemporal_load((const f32x4*)(part + (size_t)(row0 + ai * HALF + m * 16) * 16 + 4 * fq));
;         float r2[2][4];
; #pragma unroll
;         for (int ai = 0; ai < 2; ++ai)
; #pragma unroll
;             for (int m = 0; m < 4; ++m) { float s = (pv[ai][m][0] + pv[ai][m][1]) + (pv[ai][m][2] + pv[ai][m][3]); s += __shfl_xor(s, 16); s += __shfl_xor(s, 32); r2[ai][m] = 1.0f / (s * (1.0f / 1024.0f) + eps); }
; #pragma unroll
;         for (int ai = 0; ai < 2; ++ai)
; #pragma unroll
;             for (int m = 0; m < 4; ++m) { const int row = row0 + ai * HALF + m * 16; const float rr = r2[ai][m];
;                 bf16_t* rowp = O + ((size_t)u.pm * (ldc / 64) * 256 + (size_t)(row - u.pm * BM)) * 64 + (size_t)(col0 >> 6) * (256 * 64) + (col0 & 63);
; #pragma unroll
;                 for (int bj = 0; bj < 2; ++bj) { f32x4 v0 = acc[ai][bj][m][0], v1 = acc[ai][bj][m][1];
; #pragma unroll
;                     for (int e = 0; e < 4; ++e) { const float a = fmaxf(v0[e], 0.f), b = fmaxf(v1[e], 0.f); v0[e] = a * a * rr; v1[e] = b * b * rr; }
;                     u32x4 w; w.x = cvt_pk_bf16(v0[0], v0[1]); w.y = cvt_pk_bf16(v0[2], v0[3]); w.z = cvt_pk_bf16(v1[0], v1[1]); w.w = cvt_pk_bf16(v1[2], v1[3]);
;                     *(u32x4*)(rowp + (size_t)bj * (2 * 256 * 64)) = w; } }
.LBB0_537:
	v_lshl_add_u32 v128, s30, 8, v142
	v_or_b32_e32 v172, 16, v128
	v_ashrrev_i32_e32 v129, 31, v128
	v_ashrrev_i32_e32 v173, 31, v172
	v_lshlrev_b64 v[130:131], 6, v[128:129]
	v_lshlrev_b64 v[172:173], 6, v[172:173]
	v_lshl_add_u64 v[130:131], v[160:161], 0, v[130:131]
	v_lshl_add_u64 v[172:173], v[160:161], 0, v[172:173]
	global_load_dwordx4 v[176:179], v[130:131], off nt
	global_load_dwordx4 v[180:183], v[172:173], off nt
	v_or_b32_e32 v172, 32, v128
	v_ashrrev_i32_e32 v173, 31, v172
	v_or_b32_e32 v128, 48, v128
	v_lshlrev_b64 v[172:173], 6, v[172:173]
	v_ashrrev_i32_e32 v129, 31, v128
	v_lshl_add_u64 v[172:173], v[160:161], 0, v[172:173]
	v_lshlrev_b64 v[128:129], 6, v[128:129]
	global_load_dwordx4 v[184:187], v[172:173], off nt
	v_lshl_add_u64 v[128:129], v[160:161], 0, v[128:129]
	global_load_dwordx4 v[188:191], v[128:129], off nt
	v_and_b32_e32 v129, 64, v169
	v_xor_b32_e32 v128, 16, v169
	v_add_u32_e32 v129, 64, v129
	v_xor_b32_e32 v171, 32, v169
	v_cmp_lt_i32_e32 vcc, v128, v129
	s_lshl_b32 s2, s6, 8
	s_or_b32 s21, s2, s54
	v_cndmask_b32_e32 v128, v169, v128, vcc
	v_cmp_lt_i32_e32 vcc, v171, v129
	v_lshlrev_b32_e32 v174, 2, v128
	s_nop 0
	v_cndmask_b32_e32 v129, v169, v171, vcc
	v_add_co_u32_e32 v128, vcc, s47, v130
	v_lshlrev_b32_e32 v204, 2, v129
	s_nop 0
	v_addc_co_u32_e32 v129, vcc, 0, v131, vcc
	global_load_dwordx4 v[192:195], v[128:129], off nt
	global_load_dwordx4 v[196:199], v[128:129], off offset:1024 nt
	global_load_dwordx4 v[200:203], v[128:129], off offset:2048 nt
	s_nop 0
	global_load_dwordx4 v[128:131], v[128:129], off offset:3072 nt
	s_ashr_i32 s31, s30, 31
	v_max_f32_e32 v120, 0, v120
	v_mul_f32_e32 v120, v120, v120
	v_max_f32_e32 v121, 0, v121
	v_max_f32_e32 v122, 0, v122
	v_mul_f32_e32 v121, v121, v121
	v_mul_f32_e32 v122, v122, v122
	v_max_f32_e32 v124, 0, v124
	v_max_f32_e32 v123, 0, v123
	v_mul_f32_e32 v124, v124, v124
	v_mul_f32_e32 v123, v123, v123
	v_max_f32_e32 v112, 0, v112
	v_mul_f32_e32 v112, v112, v112
	v_max_f32_e32 v113, 0, v113
	v_max_f32_e32 v114, 0, v114
	v_mul_f32_e32 v113, v113, v113
	v_mul_f32_e32 v114, v114, v114
	v_max_f32_e32 v116, 0, v116
	v_mul_f32_e32 v116, v116, v116
	v_max_f32_e32 v115, 0, v115
	v_mul_f32_e32 v115, v115, v115
	v_max_f32_e32 v104, 0, v104
	v_mul_f32_e32 v104, v104, v104
	v_max_f32_e32 v105, 0, v105
	v_max_f32_e32 v106, 0, v106
	v_mul_f32_e32 v105, v105, v105
	v_mul_f32_e32 v106, v106, v106
	v_max_f32_e32 v108, 0, v108
	v_max_f32_e32 v107, 0, v107
	v_mul_f32_e32 v108, v108, v108
	v_mul_f32_e32 v107, v107, v107
	v_max_f32_e32 v96, 0, v96
	v_mul_f32_e32 v96, v96, v96
	s_waitcnt vmcnt(0)
	v_mov_b32_e32 v172, v177
	v_mov_b32_e32 v173, v178
	v_mov_b32_e32 v177, v179
	v_pk_add_f32 v[172:173], v[172:173], v[176:177]
	v_mov_b32_e32 v176, v181
	v_mov_b32_e32 v177, v182
	v_mov_b32_e32 v181, v183
	v_add_f32_e32 v171, v172, v173
	v_pk_add_f32 v[172:173], v[176:177], v[180:181]
	v_mov_b32_e32 v178, v185
	v_mov_b32_e32 v179, v186
	v_mov_b32_e32 v185, v187
	v_mov_b32_e32 v182, v189
	v_mov_b32_e32 v183, v190
	v_mov_b32_e32 v189, v191
	v_pk_add_f32 v[176:177], v[178:179], v[184:185]
	ds_bpermute_b32 v180, v174, v171
	v_add_f32_e32 v172, v172, v173
	v_pk_add_f32 v[178:179], v[182:183], v[188:189]
	v_add_f32_e32 v173, v176, v177
	ds_bpermute_b32 v177, v174, v172
	v_add_f32_e32 v176, v178, v179
	ds_bpermute_b32 v178, v174, v173
	s_waitcnt lgkmcnt(2)
	v_add_f32_e32 v171, v171, v180
	ds_bpermute_b32 v180, v204, v171
	s_waitcnt lgkmcnt(2)
	v_add_f32_e32 v172, v172, v177
	ds_bpermute_b32 v177, v204, v172
	s_waitcnt lgkmcnt(2)
	v_add_f32_e32 v173, v173, v178
	ds_bpermute_b32 v178, v204, v173
	s_waitcnt lgkmcnt(2)
	v_add_f32_e32 v171, v171, v180
	v_fmamk_f32 v171, v171, 0x3a800000, v170
	s_waitcnt lgkmcnt(1)
	v_add_f32_e32 v172, v172, v177
	v_div_scale_f32 v177, s[6:7], v171, v171, 1.0
	s_waitcnt lgkmcnt(0)
	v_add_f32_e32 v173, v173, v178
	v_fmamk_f32 v172, v172, 0x3a800000, v170
	v_fmamk_f32 v173, v173, 0x3a800000, v170
	v_rcp_f32_e32 v180, v177
	v_div_scale_f32 v181, s[6:7], v172, v172, 1.0
	ds_bpermute_b32 v179, v174, v176
	v_div_scale_f32 v183, s[8:9], v173, v173, 1.0
	v_rcp_f32_e32 v185, v181
	v_rcp_f32_e32 v186, v183
	v_fma_f32 v187, -v177, v180, 1.0
	v_div_scale_f32 v178, vcc, 1.0, v171, 1.0
	v_fmac_f32_e32 v180, v187, v180
	v_fma_f32 v187, -v181, v185, 1.0
	s_waitcnt lgkmcnt(0)
	v_add_f32_e32 v176, v176, v179
	v_div_scale_f32 v182, s[6:7], 1.0, v172, 1.0
	v_fma_f32 v188, -v183, v186, 1.0
	v_mul_f32_e32 v189, v178, v180
	v_fmac_f32_e32 v185, v187, v185
	ds_bpermute_b32 v179, v204, v176
	v_fmac_f32_e32 v186, v188, v186
	v_fma_f32 v187, -v177, v189, v178
	v_mul_f32_e32 v188, v182, v185
	v_fmac_f32_e32 v189, v187, v180
	v_fma_f32 v187, -v181, v188, v182
	v_fma_f32 v177, -v177, v189, v178
	v_fmac_f32_e32 v188, v187, v185
	v_div_fmas_f32 v177, v177, v180, v189
	v_fma_f32 v178, -v181, v188, v182
	s_mov_b64 vcc, s[6:7]
	v_div_fixup_f32 v180, v177, v171, 1.0
	v_div_fmas_f32 v171, v178, v185, v188
	v_div_scale_f32 v184, s[8:9], 1.0, v173, 1.0
	v_div_fixup_f32 v178, v171, v172, 1.0
	s_waitcnt lgkmcnt(0)
	v_add_f32_e32 v172, v176, v179
	v_mul_f32_e32 v190, v184, v186
	v_fmamk_f32 v176, v172, 0x3a800000, v170
	v_fma_f32 v171, -v183, v190, v184
	v_div_scale_f32 v177, s[6:7], v176, v176, 1.0
	v_fmac_f32_e32 v190, v171, v186
	v_rcp_f32_e32 v179, v177
	v_fma_f32 v171, -v183, v190, v184
	s_mov_b64 vcc, s[8:9]
	v_div_fmas_f32 v171, v171, v186, v190
	v_div_fixup_f32 v181, v171, v173, 1.0
	v_mov_b32_e32 v172, v193
	v_mov_b32_e32 v173, v194
	v_mov_b32_e32 v193, v195
	v_fma_f32 v171, -v177, v179, 1.0
	v_pk_add_f32 v[172:173], v[172:173], v[192:193]
	v_fmac_f32_e32 v179, v171, v179
	v_add_f32_e32 v171, v172, v173
	ds_bpermute_b32 v172, v174, v171
	v_div_scale_f32 v173, vcc, 1.0, v176, 1.0
	v_mul_f32_e32 v182, v173, v179
	v_fma_f32 v183, -v177, v182, v173
	s_waitcnt lgkmcnt(0)
; __device__ __forceinline__ unsigned cvt_pk_bf16(float lo, float hi) { unsigned r; asm volatile("v_cvt_pk_bf16_f32 %0, %1, %2" : "=v"(r) : "v"(lo), "v"(hi)); return r; }
;     __device__ __forceinline__ void operator()(const f32x4 (&acc)[2][2][4][2], const Unit& u, int wr, int wc, int fr, int fq) const {
;     ...
;             for (int m = 0; m < 4; ++m) { float s = (pv[ai][m][0] + pv[ai][m][1]) + (pv[ai][m][2] + pv[ai][m][3]); s += __shfl_xor(s, 16); s += __shfl_xor(s, 32); r2[ai][m] = 1.0f / (s * (1.0f / 1024.0f) + eps); }
; #pragma unroll
;         for (int ai = 0; ai < 2; ++ai)
; #pragma unroll
;             for (int m = 0; m < 4; ++m) { const int row = row0 + ai * HALF + m * 16; const float rr = r2[ai][m];
;                 bf16_t* rowp = O + ((size_t)u.pm * (ldc / 64) * 256 + (size_t)(row - u.pm * BM)) * 64 + (size_t)(col0 >> 6) * (256 * 64) + (col0 & 63);
; #pragma unroll
;                 for (int bj = 0; bj < 2; ++bj) { f32x4 v0 = acc[ai][bj][m][0], v1 = acc[ai][bj][m][1];
; #pragma unroll
;                     for (int e = 0; e < 4; ++e) { const float a = fmaxf(v0[e], 0.f), b = fmaxf(v1[e], 0.f); v0[e] = a * a * rr; v1[e] = b * b * rr; }
;                     u32x4 w; w.x = cvt_pk_bf16(v0[0], v0[1]); w.y = cvt_pk_bf16(v0[2], v0[3]); w.z = cvt_pk_bf16(v1[0], v1[1]); w.w = cvt_pk_bf16(v1[2], v1[3]);
;                     *(u32x4*)(rowp + (size_t)bj * (2 * 256 * 64)) = w; } }
	v_add_f32_e32 v171, v171, v172
	ds_bpermute_b32 v172, v204, v171
	v_fmac_f32_e32 v182, v183, v179
	v_fma_f32 v173, -v177, v182, v173
	v_div_fmas_f32 v173, v173, v179, v182
	v_div_fixup_f32 v179, v173, v176, 1.0
	s_waitcnt lgkmcnt(0)
	v_add_f32_e32 v171, v171, v172
	v_mov_b32_e32 v172, v197
	v_mov_b32_e32 v173, v198
	v_mov_b32_e32 v197, v199
	v_pk_add_f32 v[172:173], v[172:173], v[196:197]
	v_fmamk_f32 v171, v171, 0x3a800000, v170
	v_add_f32_e32 v172, v172, v173
	ds_bpermute_b32 v173, v174, v172
	v_div_scale_f32 v176, s[6:7], v171, v171, 1.0
	v_rcp_f32_e32 v177, v176
	s_lshl_b64 s[8:9], s[30:31], 21
	s_waitcnt lgkmcnt(0)
	v_add_f32_e32 v172, v172, v173
	ds_bpermute_b32 v173, v204, v172
	v_fma_f32 v182, -v176, v177, 1.0
	v_fmac_f32_e32 v177, v182, v177
	v_div_scale_f32 v182, vcc, 1.0, v171, 1.0
	v_mul_f32_e32 v183, v182, v177
	v_fma_f32 v184, -v176, v183, v182
	s_waitcnt lgkmcnt(0)
	v_add_f32_e32 v172, v172, v173
	v_fmac_f32_e32 v183, v184, v177
	v_fmamk_f32 v173, v172, 0x3a800000, v170
	v_fma_f32 v176, -v176, v183, v182
	v_div_scale_f32 v182, s[6:7], v173, v173, 1.0
	v_rcp_f32_e32 v184, v182
	v_div_fmas_f32 v172, v176, v177, v183
	v_mov_b32_e32 v176, v201
	v_mov_b32_e32 v177, v202
	v_mov_b32_e32 v201, v203
	v_div_fixup_f32 v172, v172, v171, 1.0
	v_fma_f32 v171, -v182, v184, 1.0
	v_pk_add_f32 v[176:177], v[176:177], v[200:201]
	v_fmac_f32_e32 v184, v171, v184
	v_add_f32_e32 v171, v176, v177
	ds_bpermute_b32 v176, v174, v171
	v_div_scale_f32 v177, vcc, 1.0, v173, 1.0
	v_mul_f32_e32 v183, v177, v184
	v_fma_f32 v185, -v182, v183, v177
	s_waitcnt lgkmcnt(0)
	v_add_f32_e32 v176, v171, v176
	v_fmac_f32_e32 v183, v185, v184
	ds_bpermute_b32 v185, v204, v176
	v_fma_f32 v171, -v182, v183, v177
	v_div_fmas_f32 v171, v171, v184, v183
	v_div_fixup_f32 v171, v171, v173, 1.0
	v_mov_b32_e32 v177, v130
	s_waitcnt lgkmcnt(0)
	v_add_f32_e32 v173, v176, v185
	v_mov_b32_e32 v176, v129
	v_mov_b32_e32 v129, v131
	v_pk_add_f32 v[128:129], v[176:177], v[128:129]
	v_fmamk_f32 v173, v173, 0x3a800000, v170
	v_add_f32_e32 v128, v128, v129
	ds_bpermute_b32 v129, v174, v128
	v_div_scale_f32 v182, s[6:7], v173, v173, 1.0
	v_rcp_f32_e32 v183, v182
	v_mul_f32_e32 v124, v124, v180
	s_waitcnt lgkmcnt(0)
	v_add_f32_e32 v128, v128, v129
	ds_bpermute_b32 v129, v204, v128
	v_fma_f32 v130, -v182, v183, 1.0
	v_fmac_f32_e32 v183, v130, v183
	v_div_scale_f32 v130, vcc, 1.0, v173, 1.0
	v_mul_f32_e32 v131, v130, v183
	s_waitcnt lgkmcnt(0)
	v_add_f32_e32 v128, v128, v129
	v_fma_f32 v174, -v182, v131, v130
	v_fmamk_f32 v128, v128, 0x3a800000, v170
	v_fmac_f32_e32 v131, v174, v183
	v_div_scale_f32 v174, s[6:7], v128, v128, 1.0
	v_rcp_f32_e32 v176, v174
	v_fma_f32 v130, -v182, v131, v130
	v_div_fmas_f32 v129, v130, v183, v131
	s_ashr_i32 s6, s21, 6
	v_fma_f32 v130, -v174, v176, 1.0
	v_fmac_f32_e32 v176, v130, v176
	v_div_scale_f32 v130, vcc, 1.0, v128, 1.0
	v_mul_f32_e32 v131, v130, v176
	v_div_fixup_f32 v129, v129, v173, 1.0
	v_fma_f32 v173, -v174, v131, v130
	s_ashr_i32 s7, s6, 31
	v_fmac_f32_e32 v131, v173, v176
	s_lshl_b64 s[6:7], s[6:7], 15
	v_fma_f32 v130, -v174, v131, v130
	s_add_u32 s8, s42, s8
	v_mul_f32_e32 v173, v120, v180
	v_max_f32_e32 v120, 0, v125
	v_div_fmas_f32 v130, v130, v176, v131
	s_addc_u32 s9, s43, s9
	v_mul_f32_e32 v125, v121, v180
	v_max_f32_e32 v121, 0, v126
	v_mul_f32_e32 v126, v122, v180
	v_max_f32_e32 v122, 0, v127
	v_div_fixup_f32 v128, v130, v128, 1.0
	v_lshl_add_u64 v[130:131], s[8:9], 0, v[144:145]
	v_mul_f32_e32 v120, v120, v120
	v_lshl_add_u64 v[130:131], v[130:131], 0, s[6:7]
	v_mul_f32_e32 v120, v120, v180
	v_mul_f32_e32 v121, v121, v121
	v_mul_f32_e32 v122, v122, v122
	v_lshl_add_u64 v[130:131], v[130:131], 0, v[140:141]
	v_mul_f32_e32 v121, v121, v180
	v_mul_f32_e32 v122, v122, v180
	v_mul_f32_e32 v123, v123, v180
	v_cvt_pk_bf16_f32 v120, v124, v120
	v_cvt_pk_bf16_f32 v121, v121, v122
	v_cvt_pk_bf16_f32 v122, v173, v125
	v_cvt_pk_bf16_f32 v123, v126, v123
	global_store_dwordx4 v[130:131], v[120:123], off
	v_mul_f32_e32 v116, v116, v180
	v_mul_f32_e32 v115, v115, v180
	v_mul_f32_e32 v120, v112, v180
	v_max_f32_e32 v112, 0, v117
	v_mul_f32_e32 v117, v113, v180
	v_max_f32_e32 v113, 0, v118
	v_mul_f32_e32 v118, v114, v180
	v_max_f32_e32 v114, 0, v119
	v_mul_f32_e32 v112, v112, v112
	v_mul_f32_e32 v112, v112, v180
	v_mul_f32_e32 v113, v113, v113
	v_mul_f32_e32 v114, v114, v114
	v_mul_f32_e32 v113, v113, v180
	v_mul_f32_e32 v114, v114, v180
	v_cvt_pk_bf16_f32 v112, v116, v112
	v_add_co_u32_e32 v116, vcc, s49, v130
	v_cvt_pk_bf16_f32 v113, v113, v114
	v_cvt_pk_bf16_f32 v114, v120, v117
	v_cvt_pk_bf16_f32 v115, v118, v115
	v_mul_f32_e32 v108, v108, v178
	s_nop 0
	v_addc_co_u32_e32 v117, vcc, 0, v131, vcc
	global_store_dwordx4 v[116:117], v[112:115], off
	v_mul_f32_e32 v107, v107, v178
	v_max_f32_e32 v97, 0, v97
	v_mul_f32_e32 v114, v104, v178
	v_max_f32_e32 v104, 0, v109
	v_mul_f32_e32 v109, v105, v178
	v_max_f32_e32 v105, 0, v110
	v_mul_f32_e32 v110, v106, v178
	v_max_f32_e32 v106, 0, v111
	v_lshl_add_u64 v[112:113], s[8:9], 0, v[146:147]
	v_mul_f32_e32 v104, v104, v104
	v_lshl_add_u64 v[112:113], v[112:113], 0, s[6:7]
	v_mul_f32_e32 v104, v104, v178
	v_mul_f32_e32 v105, v105, v105
	v_mul_f32_e32 v106, v106, v106
	v_lshl_add_u64 v[112:113], v[112:113], 0, v[140:141]
	v_mul_f32_e32 v105, v105, v178
	v_mul_f32_e32 v106, v106, v178
	v_cvt_pk_bf16_f32 v104, v108, v104
	v_max_f32_e32 v98, 0, v98
	v_cvt_pk_bf16_f32 v105, v105, v106
	v_cvt_pk_bf16_f32 v106, v114, v109
	v_cvt_pk_bf16_f32 v107, v110, v107
	global_store_dwordx4 v[112:113], v[104:107], off
	v_mul_f32_e32 v97, v97, v97
	s_nop 0
	v_mul_f32_e32 v104, v96, v178
	v_max_f32_e32 v96, 0, v101
; __device__ __forceinline__ unsigned cvt_pk_bf16(float lo, float hi) { unsigned r; asm volatile("v_cvt_pk_bf16_f32 %0, %1, %2" : "=v"(r) : "v"(lo), "v"(hi)); return r; }
;     __device__ __forceinline__ void operator()(const f32x4 (&acc)[2][2][4][2], const Unit& u, int wr, int wc, int fr, int fq) const {
;     ...
;             for (int m = 0; m < 4; ++m) { const int row = row0 + ai * HALF + m * 16; const float rr = r2[ai][m];
;                 bf16_t* rowp = O + ((size_t)u.pm * (ldc / 64) * 256 + (size_t)(row - u.pm * BM)) * 64 + (size_t)(col0 >> 6) * (256 * 64) + (col0 & 63);
; #pragma unroll
;                 for (int bj = 0; bj < 2; ++bj) { f32x4 v0 = acc[ai][bj][m][0], v1 = acc[ai][bj][m][1];
; #pragma unroll
;                     for (int e = 0; e < 4; ++e) { const float a = fmaxf(v0[e], 0.f), b = fmaxf(v1[e], 0.f); v0[e] = a * a * rr; v1[e] = b * b * rr; }
;                     u32x4 w; w.x = cvt_pk_bf16(v0[0], v0[1]); w.y = cvt_pk_bf16(v0[2], v0[3]); w.z = cvt_pk_bf16(v1[0], v1[1]); w.w = cvt_pk_bf16(v1[2], v1[3]);
;                     *(u32x4*)(rowp + (size_t)bj * (2 * 256 * 64)) = w; } }
	v_mul_f32_e32 v98, v98, v98
	v_max_f32_e32 v100, 0, v100
	v_mul_f32_e32 v101, v97, v178
	v_max_f32_e32 v97, 0, v102
	v_mul_f32_e32 v102, v98, v178
	v_max_f32_e32 v98, 0, v103
	v_mul_f32_e32 v100, v100, v100
	v_mul_f32_e32 v96, v96, v96
	v_mul_f32_e32 v100, v100, v178
	v_mul_f32_e32 v96, v96, v178
	v_mul_f32_e32 v97, v97, v97
	v_max_f32_e32 v99, 0, v99
	v_mul_f32_e32 v98, v98, v98
	v_mul_f32_e32 v97, v97, v178
	v_mul_f32_e32 v98, v98, v178
	v_mul_f32_e32 v99, v99, v99
	v_cvt_pk_bf16_f32 v96, v100, v96
	v_add_co_u32_e32 v100, vcc, s49, v112
	v_max_f32_e32 v88, 0, v88
	v_mul_f32_e32 v99, v99, v178
	v_cvt_pk_bf16_f32 v97, v97, v98
	v_cvt_pk_bf16_f32 v98, v104, v101
	v_addc_co_u32_e32 v101, vcc, 0, v113, vcc
	v_mul_f32_e32 v88, v88, v88
	v_max_f32_e32 v89, 0, v89
	v_max_f32_e32 v90, 0, v90
	v_cvt_pk_bf16_f32 v99, v102, v99
	global_store_dwordx4 v[100:101], v[96:99], off
	v_mul_f32_e32 v89, v89, v89
	v_mul_f32_e32 v90, v90, v90
	v_mul_f32_e32 v98, v88, v181
	v_max_f32_e32 v88, 0, v93
	v_mul_f32_e32 v93, v89, v181
	v_max_f32_e32 v89, 0, v94
	v_mul_f32_e32 v94, v90, v181
	v_max_f32_e32 v90, 0, v95
	v_lshl_add_u64 v[96:97], s[8:9], 0, v[148:149]
	v_max_f32_e32 v92, 0, v92
	v_mul_f32_e32 v88, v88, v88
	v_max_f32_e32 v91, 0, v91
	v_lshl_add_u64 v[96:97], v[96:97], 0, s[6:7]
	v_mul_f32_e32 v92, v92, v92
	v_mul_f32_e32 v88, v88, v181
	v_mul_f32_e32 v89, v89, v89
	v_mul_f32_e32 v90, v90, v90
	v_mul_f32_e32 v91, v91, v91
	v_max_f32_e32 v80, 0, v80
	v_lshl_add_u64 v[96:97], v[96:97], 0, v[140:141]
	v_mul_f32_e32 v92, v92, v181
	v_mul_f32_e32 v89, v89, v181
	v_mul_f32_e32 v90, v90, v181
	v_mul_f32_e32 v91, v91, v181
	v_cvt_pk_bf16_f32 v88, v92, v88
	v_mul_f32_e32 v80, v80, v80
	v_max_f32_e32 v81, 0, v81
	v_max_f32_e32 v82, 0, v82
	v_cvt_pk_bf16_f32 v89, v89, v90
	v_cvt_pk_bf16_f32 v90, v98, v93
	v_cvt_pk_bf16_f32 v91, v94, v91
	global_store_dwordx4 v[96:97], v[88:91], off
	v_mul_f32_e32 v81, v81, v81
	s_nop 0
	v_mul_f32_e32 v88, v80, v181
	v_max_f32_e32 v80, 0, v85
	v_mul_f32_e32 v82, v82, v82
	v_max_f32_e32 v84, 0, v84
	v_mul_f32_e32 v85, v81, v181
	v_max_f32_e32 v81, 0, v86
	v_mul_f32_e32 v86, v82, v181
	v_max_f32_e32 v82, 0, v87
	v_mul_f32_e32 v84, v84, v84
	v_mul_f32_e32 v80, v80, v80
	v_mul_f32_e32 v84, v84, v181
	v_mul_f32_e32 v80, v80, v181
	v_mul_f32_e32 v81, v81, v81
	v_max_f32_e32 v83, 0, v83
	v_mul_f32_e32 v82, v82, v82
	v_mul_f32_e32 v81, v81, v181
	v_mul_f32_e32 v82, v82, v181
	v_mul_f32_e32 v83, v83, v83
	v_cvt_pk_bf16_f32 v80, v84, v80
	v_add_co_u32_e32 v84, vcc, s49, v96
	v_max_f32_e32 v72, 0, v72
	v_mul_f32_e32 v83, v83, v181
	v_cvt_pk_bf16_f32 v81, v81, v82
	v_cvt_pk_bf16_f32 v82, v88, v85
	v_addc_co_u32_e32 v85, vcc, 0, v97, vcc
	v_mul_f32_e32 v72, v72, v72
	v_max_f32_e32 v73, 0, v73
	v_max_f32_e32 v74, 0, v74
	v_cvt_pk_bf16_f32 v83, v86, v83
	global_store_dwordx4 v[84:85], v[80:83], off
	v_mul_f32_e32 v73, v73, v73
	v_mul_f32_e32 v74, v74, v74
	v_mul_f32_e32 v82, v72, v179
	v_max_f32_e32 v72, 0, v77
	v_mul_f32_e32 v77, v73, v179
	v_max_f32_e32 v73, 0, v78
	v_mul_f32_e32 v78, v74, v179
	v_max_f32_e32 v74, 0, v79
	v_lshl_add_u64 v[80:81], s[8:9], 0, v[150:151]
	v_max_f32_e32 v76, 0, v76
	v_mul_f32_e32 v72, v72, v72
	v_max_f32_e32 v75, 0, v75
	v_lshl_add_u64 v[80:81], v[80:81], 0, s[6:7]
	v_mul_f32_e32 v76, v76, v76
	v_mul_f32_e32 v72, v72, v179
	v_mul_f32_e32 v73, v73, v73
	v_mul_f32_e32 v74, v74, v74
	v_mul_f32_e32 v75, v75, v75
	v_max_f32_e32 v64, 0, v64
	v_lshl_add_u64 v[80:81], v[80:81], 0, v[140:141]
	v_mul_f32_e32 v76, v76, v179
	v_mul_f32_e32 v73, v73, v179
	v_mul_f32_e32 v74, v74, v179
	v_mul_f32_e32 v75, v75, v179
	v_cvt_pk_bf16_f32 v72, v76, v72
	v_mul_f32_e32 v64, v64, v64
	v_max_f32_e32 v65, 0, v65
	v_max_f32_e32 v66, 0, v66
	v_cvt_pk_bf16_f32 v73, v73, v74
	v_cvt_pk_bf16_f32 v74, v82, v77
	v_cvt_pk_bf16_f32 v75, v78, v75
	global_store_dwordx4 v[80:81], v[72:75], off
	v_mul_f32_e32 v65, v65, v65
	s_nop 0
	v_mul_f32_e32 v72, v64, v179
	v_max_f32_e32 v64, 0, v69
	v_mul_f32_e32 v66, v66, v66
	v_max_f32_e32 v68, 0, v68
	v_mul_f32_e32 v69, v65, v179
	v_max_f32_e32 v65, 0, v70
	v_mul_f32_e32 v70, v66, v179
	v_max_f32_e32 v66, 0, v71
	v_mul_f32_e32 v68, v68, v68
	v_mul_f32_e32 v64, v64, v64
	v_mul_f32_e32 v68, v68, v179
	v_mul_f32_e32 v64, v64, v179
	v_mul_f32_e32 v65, v65, v65
	v_max_f32_e32 v67, 0, v67
	v_mul_f32_e32 v66, v66, v66
	v_mul_f32_e32 v65, v65, v179
	v_mul_f32_e32 v66, v66, v179
	v_mul_f32_e32 v67, v67, v67
	v_cvt_pk_bf16_f32 v64, v68, v64
	v_add_co_u32_e32 v68, vcc, s49, v80
	v_max_f32_e32 v56, 0, v56
	v_mul_f32_e32 v67, v67, v179
	v_cvt_pk_bf16_f32 v65, v65, v66
	v_cvt_pk_bf16_f32 v66, v72, v69
	v_addc_co_u32_e32 v69, vcc, 0, v81, vcc
	v_mul_f32_e32 v56, v56, v56
	v_max_f32_e32 v57, 0, v57
	v_max_f32_e32 v58, 0, v58
	v_cvt_pk_bf16_f32 v67, v70, v67
	global_store_dwordx4 v[68:69], v[64:67], off
	v_mul_f32_e32 v57, v57, v57
	v_mul_f32_e32 v58, v58, v58
	v_mul_f32_e32 v66, v56, v172
	v_max_f32_e32 v56, 0, v61
	v_mul_f32_e32 v61, v57, v172
	v_max_f32_e32 v57, 0, v62
	v_mul_f32_e32 v62, v58, v172
	v_max_f32_e32 v58, 0, v63
	v_lshl_add_u64 v[64:65], s[8:9], 0, v[152:153]
	v_max_f32_e32 v60, 0, v60
	v_mul_f32_e32 v56, v56, v56
	v_max_f32_e32 v59, 0, v59
	v_lshl_add_u64 v[64:65], v[64:65], 0, s[6:7]
	v_mul_f32_e32 v60, v60, v60
	v_mul_f32_e32 v56, v56, v172
	v_mul_f32_e32 v57, v57, v57
	v_mul_f32_e32 v58, v58, v58
	v_mul_f32_e32 v59, v59, v59
	v_max_f32_e32 v48, 0, v48
	v_lshl_add_u64 v[64:65], v[64:65], 0, v[140:141]
	v_mul_f32_e32 v60, v60, v172
	v_mul_f32_e32 v57, v57, v172
	v_mul_f32_e32 v58, v58, v172
	v_mul_f32_e32 v59, v59, v172
	v_cvt_pk_bf16_f32 v56, v60, v56
	v_mul_f32_e32 v48, v48, v48
	v_max_f32_e32 v49, 0, v49
; __device__ __forceinline__ unsigned cvt_pk_bf16(float lo, float hi) { unsigned r; asm volatile("v_cvt_pk_bf16_f32 %0, %1, %2" : "=v"(r) : "v"(lo), "v"(hi)); return r; }
; #define PG8_BAR __builtin_amdgcn_s_barrier()
;     __device__ __forceinline__ void operator()(const f32x4 (&acc)[2][2][4][2], const Unit& u, int wr, int wc, int fr, int fq) const {
;     ...
;             for (int m = 0; m < 4; ++m) { const int row = row0 + ai * HALF + m * 16; const float rr = r2[ai][m];
;                 bf16_t* rowp = O + ((size_t)u.pm * (ldc / 64) * 256 + (size_t)(row - u.pm * BM)) * 64 + (size_t)(col0 >> 6) * (256 * 64) + (col0 & 63);
; #pragma unroll
;                 for (int bj = 0; bj < 2; ++bj) { f32x4 v0 = acc[ai][bj][m][0], v1 = acc[ai][bj][m][1];
; #pragma unroll
;                     for (int e = 0; e < 4; ++e) { const float a = fmaxf(v0[e], 0.f), b = fmaxf(v1[e], 0.f); v0[e] = a * a * rr; v1[e] = b * b * rr; }
;                     u32x4 w; w.x = cvt_pk_bf16(v0[0], v0[1]); w.y = cvt_pk_bf16(v0[2], v0[3]); w.z = cvt_pk_bf16(v1[0], v1[1]); w.w = cvt_pk_bf16(v1[2], v1[3]);
;                     *(u32x4*)(rowp + (size_t)bj * (2 * 256 * 64)) = w; } }
; template <class Epi, class Sched, bool ALIGN_EPI = false, bool SP2 = false, bool ABLK = false>
; __device__ __forceinline__ void gemm_phase(PG8_LAS unsigned char* lds, const Gemm g, const Sched& S, const Epi& E) {
;     ...
;         if (!has_next) break;
; #pragma unroll
;         for (int a = 0; a < 2; ++a)
; #pragma unroll
;             for (int b = 0; b < 2; ++b)
; #pragma unroll
;                 for (int m = 0; m < 4; ++m)
; #pragma unroll
;                     for (int n = 0; n < 2; ++n) acc[a][b][m][n] = (f32x4){0.f, 0.f, 0.f, 0.f};
;         cur = nxt; cA = nA; cB = nB; ++ui;
;         if constexpr (ALIGN_EPI) { if (wr == 1) PG8_BAR; }
	v_max_f32_e32 v50, 0, v50
	v_cvt_pk_bf16_f32 v57, v57, v58
	v_cvt_pk_bf16_f32 v58, v66, v61
	v_cvt_pk_bf16_f32 v59, v62, v59
	global_store_dwordx4 v[64:65], v[56:59], off
	v_mul_f32_e32 v49, v49, v49
	s_nop 0
	v_mul_f32_e32 v56, v48, v172
	v_max_f32_e32 v48, 0, v53
	v_mul_f32_e32 v50, v50, v50
	v_max_f32_e32 v52, 0, v52
	v_mul_f32_e32 v53, v49, v172
	v_max_f32_e32 v49, 0, v54
	v_mul_f32_e32 v54, v50, v172
	v_max_f32_e32 v50, 0, v55
	v_mul_f32_e32 v52, v52, v52
	v_mul_f32_e32 v48, v48, v48
	v_mul_f32_e32 v52, v52, v172
	v_mul_f32_e32 v48, v48, v172
	v_mul_f32_e32 v49, v49, v49
	v_max_f32_e32 v51, 0, v51
	v_mul_f32_e32 v50, v50, v50
	v_mul_f32_e32 v49, v49, v172
	v_mul_f32_e32 v50, v50, v172
	v_mul_f32_e32 v51, v51, v51
	v_cvt_pk_bf16_f32 v48, v52, v48
	v_add_co_u32_e32 v52, vcc, s49, v64
	v_max_f32_e32 v40, 0, v40
	v_mul_f32_e32 v51, v51, v172
	v_cvt_pk_bf16_f32 v49, v49, v50
	v_cvt_pk_bf16_f32 v50, v56, v53
	v_addc_co_u32_e32 v53, vcc, 0, v65, vcc
	v_mul_f32_e32 v40, v40, v40
	v_max_f32_e32 v41, 0, v41
	v_max_f32_e32 v42, 0, v42
	v_cvt_pk_bf16_f32 v51, v54, v51
	global_store_dwordx4 v[52:53], v[48:51], off
	v_mul_f32_e32 v41, v41, v41
	v_mul_f32_e32 v42, v42, v42
	v_mul_f32_e32 v50, v40, v171
	v_max_f32_e32 v40, 0, v45
	v_mul_f32_e32 v45, v41, v171
	v_max_f32_e32 v41, 0, v46
	v_mul_f32_e32 v46, v42, v171
	v_max_f32_e32 v42, 0, v47
	v_lshl_add_u64 v[48:49], s[8:9], 0, v[154:155]
	v_max_f32_e32 v44, 0, v44
	v_mul_f32_e32 v40, v40, v40
	v_max_f32_e32 v43, 0, v43
	v_lshl_add_u64 v[48:49], v[48:49], 0, s[6:7]
	v_mul_f32_e32 v44, v44, v44
	v_mul_f32_e32 v40, v40, v171
	v_mul_f32_e32 v41, v41, v41
	v_mul_f32_e32 v42, v42, v42
	v_mul_f32_e32 v43, v43, v43
	v_max_f32_e32 v32, 0, v32
	v_lshl_add_u64 v[48:49], v[48:49], 0, v[140:141]
	v_mul_f32_e32 v44, v44, v171
	v_mul_f32_e32 v41, v41, v171
	v_mul_f32_e32 v42, v42, v171
	v_mul_f32_e32 v43, v43, v171
	v_cvt_pk_bf16_f32 v40, v44, v40
	v_mul_f32_e32 v32, v32, v32
	v_max_f32_e32 v33, 0, v33
	v_max_f32_e32 v34, 0, v34
	v_cvt_pk_bf16_f32 v41, v41, v42
	v_cvt_pk_bf16_f32 v42, v50, v45
	v_cvt_pk_bf16_f32 v43, v46, v43
	global_store_dwordx4 v[48:49], v[40:43], off
	v_mul_f32_e32 v33, v33, v33
	s_nop 0
	v_mul_f32_e32 v40, v32, v171
	v_max_f32_e32 v32, 0, v37
	v_mul_f32_e32 v34, v34, v34
	v_max_f32_e32 v36, 0, v36
	v_mul_f32_e32 v37, v33, v171
	v_max_f32_e32 v33, 0, v38
	v_mul_f32_e32 v38, v34, v171
	v_max_f32_e32 v34, 0, v39
	v_mul_f32_e32 v36, v36, v36
	v_mul_f32_e32 v32, v32, v32
	v_mul_f32_e32 v36, v36, v171
	v_mul_f32_e32 v32, v32, v171
	v_mul_f32_e32 v33, v33, v33
	v_max_f32_e32 v35, 0, v35
	v_mul_f32_e32 v34, v34, v34
	v_mul_f32_e32 v33, v33, v171
	v_mul_f32_e32 v34, v34, v171
	v_mul_f32_e32 v35, v35, v35
	v_cvt_pk_bf16_f32 v32, v36, v32
	v_add_co_u32_e32 v36, vcc, s49, v48
	v_max_f32_e32 v24, 0, v24
	v_mul_f32_e32 v35, v35, v171
	v_cvt_pk_bf16_f32 v33, v33, v34
	v_cvt_pk_bf16_f32 v34, v40, v37
	v_addc_co_u32_e32 v37, vcc, 0, v49, vcc
	v_mul_f32_e32 v24, v24, v24
	v_max_f32_e32 v25, 0, v25
	v_max_f32_e32 v26, 0, v26
	v_cvt_pk_bf16_f32 v35, v38, v35
	global_store_dwordx4 v[36:37], v[32:35], off
	v_mul_f32_e32 v25, v25, v25
	v_mul_f32_e32 v26, v26, v26
	v_mul_f32_e32 v34, v24, v129
	v_max_f32_e32 v24, 0, v29
	v_mul_f32_e32 v29, v25, v129
	v_max_f32_e32 v25, 0, v30
	v_mul_f32_e32 v30, v26, v129
	v_max_f32_e32 v26, 0, v31
	v_lshl_add_u64 v[32:33], s[8:9], 0, v[156:157]
	v_max_f32_e32 v28, 0, v28
	v_mul_f32_e32 v24, v24, v24
	v_max_f32_e32 v27, 0, v27
	v_lshl_add_u64 v[32:33], v[32:33], 0, s[6:7]
	v_mul_f32_e32 v28, v28, v28
	v_mul_f32_e32 v24, v24, v129
	v_mul_f32_e32 v25, v25, v25
	v_mul_f32_e32 v26, v26, v26
	v_mul_f32_e32 v27, v27, v27
	v_max_f32_e32 v16, 0, v16
	v_lshl_add_u64 v[32:33], v[32:33], 0, v[140:141]
	v_mul_f32_e32 v28, v28, v129
	v_mul_f32_e32 v25, v25, v129
	v_mul_f32_e32 v26, v26, v129
	v_mul_f32_e32 v27, v27, v129
	v_cvt_pk_bf16_f32 v24, v28, v24
	v_mul_f32_e32 v16, v16, v16
	v_max_f32_e32 v17, 0, v17
	v_max_f32_e32 v18, 0, v18
	v_cvt_pk_bf16_f32 v25, v25, v26
	v_cvt_pk_bf16_f32 v26, v34, v29
	v_cvt_pk_bf16_f32 v27, v30, v27
	global_store_dwordx4 v[32:33], v[24:27], off
	v_mul_f32_e32 v17, v17, v17
	s_nop 0
	v_mul_f32_e32 v24, v16, v129
	v_max_f32_e32 v16, 0, v21
	v_mul_f32_e32 v18, v18, v18
	v_max_f32_e32 v20, 0, v20
	v_mul_f32_e32 v21, v17, v129
	v_max_f32_e32 v17, 0, v22
	v_mul_f32_e32 v22, v18, v129
	v_max_f32_e32 v18, 0, v23
	v_mul_f32_e32 v20, v20, v20
	v_mul_f32_e32 v16, v16, v16
	v_mul_f32_e32 v20, v20, v129
	v_mul_f32_e32 v16, v16, v129
	v_mul_f32_e32 v17, v17, v17
	v_max_f32_e32 v19, 0, v19
	v_mul_f32_e32 v18, v18, v18
	v_mul_f32_e32 v17, v17, v129
	v_mul_f32_e32 v18, v18, v129
	v_mul_f32_e32 v19, v19, v19
	v_cvt_pk_bf16_f32 v16, v20, v16
	v_add_co_u32_e32 v20, vcc, s49, v32
	v_max_f32_e32 v8, 0, v8
	v_mul_f32_e32 v19, v19, v129
	v_cvt_pk_bf16_f32 v17, v17, v18
	v_cvt_pk_bf16_f32 v18, v24, v21
	v_addc_co_u32_e32 v21, vcc, 0, v33, vcc
	v_mul_f32_e32 v8, v8, v8
	v_max_f32_e32 v9, 0, v9
	v_max_f32_e32 v10, 0, v10
	v_cvt_pk_bf16_f32 v19, v22, v19
	global_store_dwordx4 v[20:21], v[16:19], off
	v_mul_f32_e32 v9, v9, v9
	v_mul_f32_e32 v10, v10, v10
	v_mul_f32_e32 v18, v8, v128
	v_max_f32_e32 v8, 0, v13
	v_mul_f32_e32 v13, v9, v128
	v_max_f32_e32 v9, 0, v14
	v_mul_f32_e32 v14, v10, v128
	v_max_f32_e32 v10, 0, v15
	v_lshl_add_u64 v[16:17], s[8:9], 0, v[158:159]
	v_max_f32_e32 v12, 0, v12
	v_mul_f32_e32 v8, v8, v8
	v_max_f32_e32 v11, 0, v11
	v_lshl_add_u64 v[16:17], v[16:17], 0, s[6:7]
	v_mul_f32_e32 v12, v12, v12
	v_mul_f32_e32 v8, v8, v128
	v_mul_f32_e32 v9, v9, v9
	v_mul_f32_e32 v10, v10, v10
	v_mul_f32_e32 v11, v11, v11
	v_max_f32_e32 v0, 0, v0
	v_lshl_add_u64 v[16:17], v[16:17], 0, v[140:141]
	v_mul_f32_e32 v12, v12, v128
	v_mul_f32_e32 v9, v9, v128
	v_mul_f32_e32 v10, v10, v128
	v_mul_f32_e32 v11, v11, v128
	v_cvt_pk_bf16_f32 v8, v12, v8
	v_mul_f32_e32 v0, v0, v0
	v_max_f32_e32 v1, 0, v1
	v_max_f32_e32 v2, 0, v2
	v_cvt_pk_bf16_f32 v9, v9, v10
	v_cvt_pk_bf16_f32 v10, v18, v13
	v_cvt_pk_bf16_f32 v11, v14, v11
	global_store_dwordx4 v[16:17], v[8:11], off
	v_mul_f32_e32 v1, v1, v1
	s_nop 0
	v_mul_f32_e32 v8, v0, v128
	v_max_f32_e32 v0, 0, v5
	v_mul_f32_e32 v2, v2, v2
	v_max_f32_e32 v4, 0, v4
	v_mul_f32_e32 v5, v1, v128
	v_max_f32_e32 v1, 0, v6
	v_mul_f32_e32 v6, v2, v128
	v_max_f32_e32 v2, 0, v7
	v_mul_f32_e32 v4, v4, v4
	v_mul_f32_e32 v0, v0, v0
	v_mul_f32_e32 v4, v4, v128
	v_mul_f32_e32 v0, v0, v128
	v_mul_f32_e32 v1, v1, v1
	v_mul_f32_e32 v2, v2, v2
	v_mul_f32_e32 v1, v1, v128
	v_max_f32_e32 v3, 0, v3
	v_mul_f32_e32 v2, v2, v128
	v_cvt_pk_bf16_f32 v0, v4, v0
	v_add_co_u32_e32 v4, vcc, 0x10000, v16
	v_mul_f32_e32 v3, v3, v3
	v_cvt_pk_bf16_f32 v1, v1, v2
	v_cvt_pk_bf16_f32 v2, v8, v5
	s_nop 0
	v_addc_co_u32_e32 v5, vcc, 0, v17, vcc
	v_mul_f32_e32 v3, v3, v128
	s_andn2_b64 vcc, exec, s[26:27]
	s_mov_b64 s[6:7], -1
	v_cvt_pk_bf16_f32 v3, v6, v3
	global_store_dwordx4 v[4:5], v[0:3], off
	s_cbranch_vccnz .LBB0_530
	s_andn2_b64 vcc, exec, s[14:15]
	s_cbranch_vccnz .LBB0_529
	s_barrier
	s_branch .LBB0_529
